# tile-boundary peel on G1,G2,P9: next tile SA(1,1) DMA before epilogue stores, first K-iteration waits vmcnt(22)
# baseline (speedup 1.0000x reference)
.LBB0_357:
	s_add_u32 s8, s54, 0x8000000
	s_addc_u32 s9, s55, 0
	s_lshl_b32 s10, s10, 5
	s_and_b32 s19, s10, 0x60
	s_mov_b64 s[10:11], 0x80
	s_add_i32 m0, s34, 0x18000
	v_lshl_add_u64 v[8:9], v[8:9], 0, s[10:11]
	s_lshl_b32 s18, s1, 13
	s_waitcnt vmcnt(4)
	s_barrier
	global_load_lds_dwordx4 v[8:9], off
	v_lshl_add_u64 v[6:7], v[6:7], 0, s[10:11]
	s_add_i32 m0, s34, 0x1a000
	s_add_i32 s62, s34, 0x8000
	s_add_i32 s63, s34, 0xa000
	global_load_lds_dwordx4 v[6:7], off
	v_lshl_add_u64 v[4:5], v[4:5], 0, s[10:11]
	s_mov_b32 m0, s62
	s_add_u32 s16, s46, 0x80080
	global_load_lds_dwordx4 v[4:5], off
	v_lshl_add_u64 v[2:3], v[2:3], 0, s[10:11]
	s_mov_b32 m0, s63
	s_addc_u32 s17, s47, 0
	global_load_lds_dwordx4 v[2:3], off
	s_add_i32 m0, s34, 0x1c000
	v_lshl_add_u64 v[2:3], s[16:17], 0, v[132:133]
	global_load_lds_dwordx4 v[2:3], off
	v_lshl_add_u64 v[2:3], s[16:17], 0, v[136:137]
	s_add_i32 m0, s34, 0x1e000
	v_lshlrev_b32_e32 v4, 12, v152
	global_load_lds_dwordx4 v[2:3], off
	v_lshlrev_b32_e32 v3, 2, v1
	v_lshl_or_b32 v2, v1, 6, v155
	v_and_b32_e32 v3, 32, v3
	v_bitop3_b32 v2, v2, s18, v3 bitop3:0xde
	v_lshlrev_b32_e32 v3, 9, v151
	v_and_b32_e32 v3, 0x70000, v3
	v_or3_b32 v3, v150, v3, v4
	v_add_u32_e32 v138, v3, v147
	v_lshlrev_b32_e32 v3, 5, v153
	s_waitcnt vmcnt(6)
	v_and_b32_e32 v3, 0x70000, v3
	v_lshl_or_b32 v155, s19, 7, v156
	v_or3_b32 v3, v150, v3, v4
	s_add_i32 s65, 0, 0x10000
	s_add_i32 s66, 0, 0x14000
	s_sext_i32_i8 s71, s0
	v_lshl_or_b32 v157, s1, 6, v1
	s_ashr_i32 s64, s28, 31
	v_or_b32_e32 v154, s19, v154
	v_mov_b32_e32 v139, v133
	v_add_u32_e32 v140, v3, v147
	v_mov_b32_e32 v141, v133
	v_mov_b64_e32 v[142:143], 0x400
	v_mov_b64_e32 v[144:145], 0x3ff
	v_add_u32_e32 v150, s65, v155
	v_add_u32_e32 v151, 0, v2
	v_add_u32_e32 v152, s66, v155
	s_mov_b32 s67, 0x80000
	s_mov_b64 s[16:17], 0x90000
	s_mov_b32 s68, 0x90000
	s_mov_b64 s[18:19], 0xa0000
	s_mov_b32 s69, 0xa0000
	s_mov_b64 s[24:25], 0xb0000
	s_mov_b32 s70, 0xb0000
	s_barrier
	s_mov_b32 s99, 0

.LBB0_364:
	s_ashr_i32 s37, s36, 31
	v_cmp_lt_i64_e32 vcc, s[38:39], v[142:143]
	s_lshl_b64 s[38:39], s[36:37], 20
	s_add_u32 s38, s56, s38
	s_addc_u32 s39, s57, s39
	s_and_b64 s[40:41], vcc, exec
	s_cselect_b32 s37, s39, s45
	s_cselect_b32 s72, s38, s44
	s_ashr_i32 s27, s26, 31
	s_lshl_b64 s[40:41], s[26:27], 20
	s_add_u32 s40, s30, s40
	s_addc_u32 s41, s31, s41
	s_and_b64 s[50:51], vcc, exec
	s_cselect_b32 s27, s41, s47
	s_cselect_b32 s73, s40, s46
	s_add_u32 s44, s44, 0x80080
	s_addc_u32 s45, s45, 0
	s_add_u32 s74, s46, 0x100
	v_mov_b32_e32 v2, 0
	s_addc_u32 s75, s47, 0
	s_mov_b32 s76, -2
	v_mov_b32_e32 v3, v2
	v_mov_b32_e32 v4, v2
	v_mov_b32_e32 v5, v2
	v_mov_b32_e32 v6, v2
	v_mov_b32_e32 v7, v2
	v_mov_b32_e32 v8, v2
	v_mov_b32_e32 v9, v2
	v_mov_b32_e32 v10, v2
	v_mov_b32_e32 v11, v2
	v_mov_b32_e32 v12, v2
	v_mov_b32_e32 v13, v2
	v_mov_b32_e32 v18, v2
	v_mov_b32_e32 v19, v2
	v_mov_b32_e32 v20, v2
	v_mov_b32_e32 v21, v2
	v_mov_b32_e32 v26, v2
	v_mov_b32_e32 v27, v2
	v_mov_b32_e32 v28, v2
	v_mov_b32_e32 v29, v2
	v_mov_b32_e32 v34, v2
	v_mov_b32_e32 v35, v2
	v_mov_b32_e32 v36, v2
	v_mov_b32_e32 v37, v2
	v_mov_b32_e32 v42, v2
	v_mov_b32_e32 v43, v2
	v_mov_b32_e32 v44, v2
	v_mov_b32_e32 v45, v2
	v_mov_b32_e32 v50, v2
	v_mov_b32_e32 v51, v2
	v_mov_b32_e32 v52, v2
	v_mov_b32_e32 v53, v2
	v_mov_b32_e32 v14, v2
	v_mov_b32_e32 v15, v2
	v_mov_b32_e32 v16, v2
	v_mov_b32_e32 v17, v2
	v_mov_b32_e32 v22, v2
	v_mov_b32_e32 v23, v2
	v_mov_b32_e32 v24, v2
	v_mov_b32_e32 v25, v2
	v_mov_b32_e32 v30, v2
	v_mov_b32_e32 v31, v2
	v_mov_b32_e32 v32, v2
	v_mov_b32_e32 v33, v2
	v_mov_b32_e32 v38, v2
	v_mov_b32_e32 v39, v2
	v_mov_b32_e32 v40, v2
	v_mov_b32_e32 v41, v2
	v_mov_b32_e32 v46, v2
	v_mov_b32_e32 v47, v2
	v_mov_b32_e32 v48, v2
	v_mov_b32_e32 v49, v2
	v_mov_b32_e32 v54, v2
	v_mov_b32_e32 v55, v2
	v_mov_b32_e32 v56, v2
	v_mov_b32_e32 v57, v2
	v_mov_b32_e32 v58, v2
	v_mov_b32_e32 v59, v2
	v_mov_b32_e32 v60, v2
	v_mov_b32_e32 v61, v2
	v_mov_b32_e32 v62, v2
	v_mov_b32_e32 v63, v2
	v_mov_b32_e32 v64, v2
	v_mov_b32_e32 v65, v2
	v_mov_b32_e32 v66, v2
	v_mov_b32_e32 v67, v2
	v_mov_b32_e32 v68, v2
	v_mov_b32_e32 v69, v2
	v_mov_b32_e32 v70, v2
	v_mov_b32_e32 v71, v2
	v_mov_b32_e32 v72, v2
	v_mov_b32_e32 v73, v2
	v_mov_b32_e32 v78, v2
	v_mov_b32_e32 v79, v2
	v_mov_b32_e32 v80, v2
	v_mov_b32_e32 v81, v2
	v_mov_b32_e32 v86, v2
	v_mov_b32_e32 v87, v2
	v_mov_b32_e32 v88, v2
	v_mov_b32_e32 v89, v2
	v_mov_b32_e32 v94, v2
	v_mov_b32_e32 v95, v2
	v_mov_b32_e32 v96, v2
	v_mov_b32_e32 v97, v2
	v_mov_b32_e32 v102, v2
	v_mov_b32_e32 v103, v2
	v_mov_b32_e32 v104, v2
	v_mov_b32_e32 v105, v2
	v_mov_b32_e32 v110, v2
	v_mov_b32_e32 v111, v2
	v_mov_b32_e32 v112, v2
	v_mov_b32_e32 v113, v2
	v_mov_b32_e32 v118, v2
	v_mov_b32_e32 v119, v2
	v_mov_b32_e32 v120, v2
	v_mov_b32_e32 v121, v2
	v_mov_b32_e32 v74, v2
	v_mov_b32_e32 v75, v2
	v_mov_b32_e32 v76, v2
	v_mov_b32_e32 v77, v2
	v_mov_b32_e32 v82, v2
	v_mov_b32_e32 v83, v2
	v_mov_b32_e32 v84, v2
	v_mov_b32_e32 v85, v2
	v_mov_b32_e32 v90, v2
	v_mov_b32_e32 v91, v2
	v_mov_b32_e32 v92, v2
	v_mov_b32_e32 v93, v2
	v_mov_b32_e32 v98, v2
	v_mov_b32_e32 v99, v2
	v_mov_b32_e32 v100, v2
	v_mov_b32_e32 v101, v2
	v_mov_b32_e32 v106, v2
	v_mov_b32_e32 v107, v2
	v_mov_b32_e32 v108, v2
	v_mov_b32_e32 v109, v2
	v_mov_b32_e32 v114, v2
	v_mov_b32_e32 v115, v2
	v_mov_b32_e32 v116, v2
	v_mov_b32_e32 v117, v2
	v_mov_b32_e32 v122, v2
	v_mov_b32_e32 v123, v2
	v_mov_b32_e32 v124, v2
	v_mov_b32_e32 v125, v2
	v_mov_b32_e32 v126, v2
	v_mov_b32_e32 v127, v2
	v_mov_b32_e32 v128, v2
	v_mov_b32_e32 v129, v2
	s_cmp_eq_u32 s99, 0
	s_cbranch_scc1 .LBB0_365
	ds_read_b128 v[158:161], v150
	ds_read_b128 v[162:165], v150 offset:1024
	ds_read_b128 v[166:169], v150 offset:2048
	ds_read_b128 v[170:173], v150 offset:3072
	s_add_u32 s46, s44, 0xfff80080
	s_addc_u32 s47, s45, -1
	s_cmp_eq_u32 s76, 28
	s_cselect_b32 s51, s37, s47
	s_cselect_b32 s50, s72, s46
	s_cselect_b32 s47, s27, s75
	s_cselect_b32 s46, s73, s74
	v_lshl_add_u64 v[148:149], s[44:45], 0, v[138:139]
	s_add_i32 m0, s34, 0xc000
	ds_read_b128 v[174:177], v151
	ds_read_b128 v[178:181], v151 offset:1024
	ds_read_b128 v[182:185], v151 offset:2048
	ds_read_b128 v[186:189], v151 offset:3072
	ds_read_b128 v[190:193], v151 offset:4096
	ds_read_b128 v[194:197], v151 offset:5120
	ds_read_b128 v[204:207], v151 offset:6144
	ds_read_b128 v[208:211], v151 offset:7168
	v_lshl_add_u64 v[148:149], s[44:45], 0, v[140:141]
	s_add_i32 m0, s34, 0xe000
	s_nop 0
	s_waitcnt lgkmcnt(8)
	s_barrier
	s_waitcnt lgkmcnt(0)
	s_setprio 1
	s_waitcnt lgkmcnt(0)
	v_mfma_f32_16x16x32_bf16 v[126:129], v[158:161], v[174:177], v[126:129]
	v_mfma_f32_16x16x32_bf16 v[122:125], v[166:169], v[174:177], v[122:125]
	v_mfma_f32_16x16x32_bf16 v[114:117], v[158:161], v[182:185], v[114:117]
	v_mfma_f32_16x16x32_bf16 v[106:109], v[166:169], v[182:185], v[106:109]
	v_mfma_f32_16x16x32_bf16 v[98:101], v[158:161], v[190:193], v[98:101]
	v_mfma_f32_16x16x32_bf16 v[90:93], v[166:169], v[190:193], v[90:93]
	v_mfma_f32_16x16x32_bf16 v[82:85], v[158:161], v[204:207], v[82:85]
	v_mfma_f32_16x16x32_bf16 v[74:77], v[166:169], v[204:207], v[74:77]
	v_mfma_f32_16x16x32_bf16 v[126:129], v[162:165], v[178:181], v[126:129]
	v_mfma_f32_16x16x32_bf16 v[122:125], v[170:173], v[178:181], v[122:125]
	v_mfma_f32_16x16x32_bf16 v[114:117], v[162:165], v[186:189], v[114:117]
	v_mfma_f32_16x16x32_bf16 v[106:109], v[170:173], v[186:189], v[106:109]
	v_mfma_f32_16x16x32_bf16 v[98:101], v[162:165], v[194:197], v[98:101]
	v_mfma_f32_16x16x32_bf16 v[90:93], v[170:173], v[194:197], v[90:93]
	v_mfma_f32_16x16x32_bf16 v[82:85], v[162:165], v[208:211], v[82:85]
	v_mfma_f32_16x16x32_bf16 v[74:77], v[170:173], v[208:211], v[74:77]
	s_setprio 0
	s_barrier
	s_add_i32 s77, s65, s33
	v_lshl_add_u64 v[148:149], s[46:47], 0, v[132:133]
	s_mov_b32 m0, s77
	ds_read_b128 v[212:215], v152
	ds_read_b128 v[216:219], v152 offset:1024
	ds_read_b128 v[220:223], v152 offset:2048
	ds_read_b128 v[224:227], v152 offset:3072
	global_load_lds_dwordx4 v[148:149], off
	v_lshl_add_u64 v[198:199], s[46:47], 0, v[136:137]
	s_add_i32 m0, s77, 0x2000
	s_nop 0
	global_load_lds_dwordx4 v[198:199], off
	s_barrier
	s_waitcnt lgkmcnt(0)
	s_setprio 1
	s_waitcnt lgkmcnt(0)
	v_mfma_f32_16x16x32_bf16 v[118:121], v[212:215], v[174:177], v[118:121]
	v_mfma_f32_16x16x32_bf16 v[110:113], v[220:223], v[174:177], v[110:113]
	v_mfma_f32_16x16x32_bf16 v[102:105], v[212:215], v[182:185], v[102:105]
	v_mfma_f32_16x16x32_bf16 v[94:97], v[220:223], v[182:185], v[94:97]
	v_mfma_f32_16x16x32_bf16 v[86:89], v[212:215], v[190:193], v[86:89]
	v_mfma_f32_16x16x32_bf16 v[78:81], v[220:223], v[190:193], v[78:81]
	v_mfma_f32_16x16x32_bf16 v[70:73], v[212:215], v[204:207], v[70:73]
	v_mfma_f32_16x16x32_bf16 v[66:69], v[220:223], v[204:207], v[66:69]
	v_mfma_f32_16x16x32_bf16 v[118:121], v[216:219], v[178:181], v[118:121]
	v_mfma_f32_16x16x32_bf16 v[110:113], v[224:227], v[178:181], v[110:113]
	v_mfma_f32_16x16x32_bf16 v[102:105], v[216:219], v[186:189], v[102:105]
	v_mfma_f32_16x16x32_bf16 v[94:97], v[224:227], v[186:189], v[94:97]
	v_mfma_f32_16x16x32_bf16 v[86:89], v[216:219], v[194:197], v[86:89]
	v_mfma_f32_16x16x32_bf16 v[78:81], v[224:227], v[194:197], v[78:81]
	v_mfma_f32_16x16x32_bf16 v[70:73], v[216:219], v[208:211], v[70:73]
	v_mfma_f32_16x16x32_bf16 v[66:69], v[224:227], v[208:211], v[66:69]
	s_setprio 0
	s_mov_b32 m0, s34
	v_lshl_add_u64 v[228:229], s[50:51], 0, v[130:131]
	s_barrier
	ds_read_b128 v[174:177], v151 offset:16384
	ds_read_b128 v[178:181], v151 offset:17408
	ds_read_b128 v[182:185], v151 offset:18432
	ds_read_b128 v[186:189], v151 offset:19456
	ds_read_b128 v[190:193], v151 offset:20480
	ds_read_b128 v[194:197], v151 offset:21504
	ds_read_b128 v[204:207], v151 offset:22528
	ds_read_b128 v[208:211], v151 offset:23552
	global_load_lds_dwordx4 v[228:229], off
	v_lshl_add_u64 v[230:231], s[50:51], 0, v[134:135]
	s_mov_b32 m0, s35
	s_nop 0
	global_load_lds_dwordx4 v[230:231], off
	s_barrier
	s_waitcnt lgkmcnt(0)
	s_setprio 1
	s_waitcnt lgkmcnt(0)
	v_mfma_f32_16x16x32_bf16 v[62:65], v[158:161], v[174:177], v[62:65]
	v_mfma_f32_16x16x32_bf16 v[58:61], v[166:169], v[174:177], v[58:61]
	v_mfma_f32_16x16x32_bf16 v[54:57], v[158:161], v[182:185], v[54:57]
	v_mfma_f32_16x16x32_bf16 v[46:49], v[166:169], v[182:185], v[46:49]
	v_mfma_f32_16x16x32_bf16 v[38:41], v[158:161], v[190:193], v[38:41]
	v_mfma_f32_16x16x32_bf16 v[30:33], v[166:169], v[190:193], v[30:33]
	v_mfma_f32_16x16x32_bf16 v[22:25], v[158:161], v[204:207], v[22:25]
	v_mfma_f32_16x16x32_bf16 v[14:17], v[166:169], v[204:207], v[14:17]
	v_mfma_f32_16x16x32_bf16 v[62:65], v[162:165], v[178:181], v[62:65]
	v_mfma_f32_16x16x32_bf16 v[58:61], v[170:173], v[178:181], v[58:61]
	v_mfma_f32_16x16x32_bf16 v[54:57], v[162:165], v[186:189], v[54:57]
	v_mfma_f32_16x16x32_bf16 v[46:49], v[170:173], v[186:189], v[46:49]
	v_mfma_f32_16x16x32_bf16 v[38:41], v[162:165], v[194:197], v[38:41]
	v_mfma_f32_16x16x32_bf16 v[30:33], v[170:173], v[194:197], v[30:33]
	v_mfma_f32_16x16x32_bf16 v[22:25], v[162:165], v[208:211], v[22:25]
	v_mfma_f32_16x16x32_bf16 v[14:17], v[170:173], v[208:211], v[14:17]
	s_setprio 0
	s_barrier
	s_add_u32 s78, s46, 0x80000
	s_addc_u32 s79, s47, 0
	s_add_i32 s77, s66, s33
	v_lshl_add_u64 v[158:159], s[78:79], 0, v[132:133]
	s_mov_b32 m0, s77
	s_nop 0
	global_load_lds_dwordx4 v[158:159], off
	v_lshl_add_u64 v[158:159], s[78:79], 0, v[136:137]
	s_add_i32 m0, s77, 0x2000
	s_nop 0
	global_load_lds_dwordx4 v[158:159], off
	s_waitcnt vmcnt(22)
	s_barrier
	s_setprio 1
	v_mfma_f32_16x16x32_bf16 v[50:53], v[212:215], v[174:177], v[50:53]
	v_mfma_f32_16x16x32_bf16 v[42:45], v[220:223], v[174:177], v[42:45]
	v_mfma_f32_16x16x32_bf16 v[34:37], v[212:215], v[182:185], v[34:37]
	v_mfma_f32_16x16x32_bf16 v[26:29], v[220:223], v[182:185], v[26:29]
	v_mfma_f32_16x16x32_bf16 v[18:21], v[212:215], v[190:193], v[18:21]
	v_mfma_f32_16x16x32_bf16 v[10:13], v[220:223], v[190:193], v[10:13]
	v_mfma_f32_16x16x32_bf16 v[6:9], v[212:215], v[204:207], v[6:9]
	v_mfma_f32_16x16x32_bf16 v[2:5], v[220:223], v[204:207], v[2:5]
	v_mfma_f32_16x16x32_bf16 v[50:53], v[216:219], v[178:181], v[50:53]
	v_mfma_f32_16x16x32_bf16 v[42:45], v[224:227], v[178:181], v[42:45]
	v_mfma_f32_16x16x32_bf16 v[34:37], v[216:219], v[186:189], v[34:37]
	v_mfma_f32_16x16x32_bf16 v[26:29], v[224:227], v[186:189], v[26:29]
	v_mfma_f32_16x16x32_bf16 v[18:21], v[216:219], v[194:197], v[18:21]
	v_mfma_f32_16x16x32_bf16 v[10:13], v[224:227], v[194:197], v[10:13]
	v_mfma_f32_16x16x32_bf16 v[6:9], v[216:219], v[208:211], v[6:9]
	v_mfma_f32_16x16x32_bf16 v[2:5], v[224:227], v[208:211], v[2:5]
	s_setprio 0
	s_add_i32 s77, 0, 0x18000
	v_add_u32_e32 v153, s77, v155
	s_barrier
	s_branch .Ltb_mid_g2

.Ltb_mid_g2:
	ds_read_b128 v[158:161], v153
	ds_read_b128 v[162:165], v153 offset:1024
	ds_read_b128 v[166:169], v153 offset:2048
	ds_read_b128 v[170:173], v153 offset:3072
	s_add_u32 s50, s50, 0x80000
	s_addc_u32 s51, s51, 0
	s_mov_b32 m0, s43
	v_lshl_add_u64 v[212:213], s[50:51], 0, v[130:131]
	ds_read_b128 v[174:177], v151 offset:32768
	ds_read_b128 v[178:181], v151 offset:33792
	ds_read_b128 v[182:185], v151 offset:34816
	ds_read_b128 v[186:189], v151 offset:35840
	ds_read_b128 v[190:193], v151 offset:36864
	ds_read_b128 v[194:197], v151 offset:37888
	ds_read_b128 v[204:207], v151 offset:38912
	ds_read_b128 v[208:211], v151 offset:39936
	global_load_lds_dwordx4 v[212:213], off
	v_lshl_add_u64 v[212:213], s[50:51], 0, v[134:135]
	s_mov_b32 m0, s60
	s_nop 0
	global_load_lds_dwordx4 v[212:213], off
	s_waitcnt lgkmcnt(8)
	s_barrier
	s_waitcnt lgkmcnt(0)
	s_setprio 1
	s_waitcnt lgkmcnt(0)
	v_mfma_f32_16x16x32_bf16 v[126:129], v[158:161], v[174:177], v[126:129]
	v_mfma_f32_16x16x32_bf16 v[122:125], v[166:169], v[174:177], v[122:125]
	v_mfma_f32_16x16x32_bf16 v[114:117], v[158:161], v[182:185], v[114:117]
	v_mfma_f32_16x16x32_bf16 v[106:109], v[166:169], v[182:185], v[106:109]
	v_mfma_f32_16x16x32_bf16 v[98:101], v[158:161], v[190:193], v[98:101]
	v_mfma_f32_16x16x32_bf16 v[90:93], v[166:169], v[190:193], v[90:93]
	v_mfma_f32_16x16x32_bf16 v[82:85], v[158:161], v[204:207], v[82:85]
	v_mfma_f32_16x16x32_bf16 v[74:77], v[166:169], v[204:207], v[74:77]
	v_mfma_f32_16x16x32_bf16 v[126:129], v[162:165], v[178:181], v[126:129]
	v_mfma_f32_16x16x32_bf16 v[122:125], v[170:173], v[178:181], v[122:125]
	v_mfma_f32_16x16x32_bf16 v[114:117], v[162:165], v[186:189], v[114:117]
	v_mfma_f32_16x16x32_bf16 v[106:109], v[170:173], v[186:189], v[106:109]
	v_mfma_f32_16x16x32_bf16 v[98:101], v[162:165], v[194:197], v[98:101]
	v_mfma_f32_16x16x32_bf16 v[90:93], v[170:173], v[194:197], v[90:93]
	v_mfma_f32_16x16x32_bf16 v[82:85], v[162:165], v[208:211], v[82:85]
	v_mfma_f32_16x16x32_bf16 v[74:77], v[170:173], v[208:211], v[74:77]
	s_setprio 0
	s_barrier
	s_add_i32 s50, 0, 0x1c000
	s_add_i32 s51, s77, s33
	v_add_u32_e32 v153, s50, v155
	v_lshl_add_u64 v[148:149], v[148:149], 0, s[10:11]
	s_mov_b32 m0, s51
	ds_read_b128 v[212:215], v153
	ds_read_b128 v[216:219], v153 offset:1024
	ds_read_b128 v[220:223], v153 offset:2048
	ds_read_b128 v[224:227], v153 offset:3072
	global_load_lds_dwordx4 v[148:149], off
	v_lshl_add_u64 v[148:149], v[198:199], 0, s[10:11]
	s_add_i32 m0, s51, 0x2000
	s_nop 0
	global_load_lds_dwordx4 v[148:149], off
	s_barrier
	s_waitcnt lgkmcnt(0)
	s_setprio 1
	s_waitcnt lgkmcnt(0)
	v_mfma_f32_16x16x32_bf16 v[118:121], v[212:215], v[174:177], v[118:121]
	v_mfma_f32_16x16x32_bf16 v[110:113], v[220:223], v[174:177], v[110:113]
	v_mfma_f32_16x16x32_bf16 v[102:105], v[212:215], v[182:185], v[102:105]
	v_mfma_f32_16x16x32_bf16 v[94:97], v[220:223], v[182:185], v[94:97]
	v_mfma_f32_16x16x32_bf16 v[86:89], v[212:215], v[190:193], v[86:89]
	v_mfma_f32_16x16x32_bf16 v[78:81], v[220:223], v[190:193], v[78:81]
	v_mfma_f32_16x16x32_bf16 v[70:73], v[212:215], v[204:207], v[70:73]
	v_mfma_f32_16x16x32_bf16 v[66:69], v[220:223], v[204:207], v[66:69]
	v_mfma_f32_16x16x32_bf16 v[118:121], v[216:219], v[178:181], v[118:121]
	v_mfma_f32_16x16x32_bf16 v[110:113], v[224:227], v[178:181], v[110:113]
	v_mfma_f32_16x16x32_bf16 v[102:105], v[216:219], v[186:189], v[102:105]
	v_mfma_f32_16x16x32_bf16 v[94:97], v[224:227], v[186:189], v[94:97]
	v_mfma_f32_16x16x32_bf16 v[86:89], v[216:219], v[194:197], v[86:89]
	v_mfma_f32_16x16x32_bf16 v[78:81], v[224:227], v[194:197], v[78:81]
	v_mfma_f32_16x16x32_bf16 v[70:73], v[216:219], v[208:211], v[70:73]
	v_mfma_f32_16x16x32_bf16 v[66:69], v[224:227], v[208:211], v[66:69]
	s_setprio 0
	s_mov_b32 m0, s62
	v_lshl_add_u64 v[148:149], v[228:229], 0, s[10:11]
	s_barrier
	ds_read_b128 v[174:177], v151 offset:49152
	ds_read_b128 v[178:181], v151 offset:50176
	ds_read_b128 v[182:185], v151 offset:51200
	ds_read_b128 v[186:189], v151 offset:52224
	ds_read_b128 v[190:193], v151 offset:53248
	ds_read_b128 v[194:197], v151 offset:54272
	ds_read_b128 v[204:207], v151 offset:55296
	ds_read_b128 v[208:211], v151 offset:56320
	global_load_lds_dwordx4 v[148:149], off
	v_lshl_add_u64 v[148:149], v[230:231], 0, s[10:11]
	s_mov_b32 m0, s63
	s_nop 0
	global_load_lds_dwordx4 v[148:149], off
	s_barrier
	s_waitcnt lgkmcnt(0)
	s_setprio 1
	s_waitcnt lgkmcnt(0)
	v_mfma_f32_16x16x32_bf16 v[62:65], v[158:161], v[174:177], v[62:65]
	v_mfma_f32_16x16x32_bf16 v[58:61], v[166:169], v[174:177], v[58:61]
	v_mfma_f32_16x16x32_bf16 v[54:57], v[158:161], v[182:185], v[54:57]
	v_mfma_f32_16x16x32_bf16 v[46:49], v[166:169], v[182:185], v[46:49]
	v_mfma_f32_16x16x32_bf16 v[38:41], v[158:161], v[190:193], v[38:41]
	v_mfma_f32_16x16x32_bf16 v[30:33], v[166:169], v[190:193], v[30:33]
	v_mfma_f32_16x16x32_bf16 v[22:25], v[158:161], v[204:207], v[22:25]
	v_mfma_f32_16x16x32_bf16 v[14:17], v[166:169], v[204:207], v[14:17]
	v_mfma_f32_16x16x32_bf16 v[62:65], v[162:165], v[178:181], v[62:65]
	v_mfma_f32_16x16x32_bf16 v[58:61], v[170:173], v[178:181], v[58:61]
	v_mfma_f32_16x16x32_bf16 v[54:57], v[162:165], v[186:189], v[54:57]
	v_mfma_f32_16x16x32_bf16 v[46:49], v[170:173], v[186:189], v[46:49]
	v_mfma_f32_16x16x32_bf16 v[38:41], v[162:165], v[194:197], v[38:41]
	v_mfma_f32_16x16x32_bf16 v[30:33], v[170:173], v[194:197], v[30:33]
	v_mfma_f32_16x16x32_bf16 v[22:25], v[162:165], v[208:211], v[22:25]
	v_mfma_f32_16x16x32_bf16 v[14:17], v[170:173], v[208:211], v[14:17]
	s_setprio 0
	s_barrier
	s_add_u32 s46, s46, 0x80080
	s_addc_u32 s47, s47, 0
	s_add_i32 s50, s50, s33
	v_lshl_add_u64 v[148:149], s[46:47], 0, v[132:133]
	s_mov_b32 m0, s50
	s_nop 0
	global_load_lds_dwordx4 v[148:149], off
	v_lshl_add_u64 v[148:149], s[46:47], 0, v[136:137]
	s_add_i32 m0, s50, 0x2000
	s_nop 0
	global_load_lds_dwordx4 v[148:149], off
	s_waitcnt vmcnt(6)
	s_barrier
	s_setprio 1
	v_mfma_f32_16x16x32_bf16 v[50:53], v[212:215], v[174:177], v[50:53]
	v_mfma_f32_16x16x32_bf16 v[42:45], v[220:223], v[174:177], v[42:45]
	v_mfma_f32_16x16x32_bf16 v[34:37], v[212:215], v[182:185], v[34:37]
	v_mfma_f32_16x16x32_bf16 v[26:29], v[220:223], v[182:185], v[26:29]
	v_mfma_f32_16x16x32_bf16 v[18:21], v[212:215], v[190:193], v[18:21]
	v_mfma_f32_16x16x32_bf16 v[10:13], v[220:223], v[190:193], v[10:13]
	v_mfma_f32_16x16x32_bf16 v[6:9], v[212:215], v[204:207], v[6:9]
	v_mfma_f32_16x16x32_bf16 v[2:5], v[220:223], v[204:207], v[2:5]
	v_mfma_f32_16x16x32_bf16 v[50:53], v[216:219], v[178:181], v[50:53]
	v_mfma_f32_16x16x32_bf16 v[42:45], v[224:227], v[178:181], v[42:45]
	v_mfma_f32_16x16x32_bf16 v[34:37], v[216:219], v[186:189], v[34:37]
	v_mfma_f32_16x16x32_bf16 v[26:29], v[224:227], v[186:189], v[26:29]
	v_mfma_f32_16x16x32_bf16 v[18:21], v[216:219], v[194:197], v[18:21]
	v_mfma_f32_16x16x32_bf16 v[10:13], v[224:227], v[194:197], v[10:13]
	v_mfma_f32_16x16x32_bf16 v[6:9], v[216:219], v[208:211], v[6:9]
	v_mfma_f32_16x16x32_bf16 v[2:5], v[224:227], v[208:211], v[2:5]
	s_setprio 0
	s_add_i32 s76, s76, 2
	s_add_u32 s44, s44, 0x100
	s_addc_u32 s45, s45, 0
	s_add_u32 s74, s74, 0x100
	s_addc_u32 s75, s75, 0
	s_cmp_gt_u32 s76, 29
	s_barrier
	s_cbranch_scc0 .LBB0_365
	s_add_u32 s100, s72, 0x80080
	s_addc_u32 s101, s37, 0
	v_lshl_add_u64 v[148:149], s[100:101], 0, v[138:139]
	s_add_i32 m0, s34, 0xc000
	s_nop 0
	global_load_lds_dwordx4 v[148:149], off
	v_lshl_add_u64 v[148:149], s[100:101], 0, v[140:141]
	s_add_i32 m0, s34, 0xe000
	s_nop 0
	global_load_lds_dwordx4 v[148:149], off
	s_mov_b32 s99, 1
	v_lshl_add_u32 v158, s42, 8, v157
	v_lshl_or_b32 v148, s71, 8, v154
	v_ashrrev_i32_e32 v159, 31, v158
	v_ashrrev_i32_e32 v149, 31, v148
	v_lshlrev_b64 v[160:161], 12, v[158:159]
	v_lshl_add_u64 v[160:161], s[8:9], 0, v[160:161]
	v_lshlrev_b64 v[162:163], 1, v[148:149]
	v_lshl_add_u64 v[148:149], v[160:161], 0, v[162:163]
	v_cvt_pk_bf16_f32 v126, v126, v127
	v_cvt_pk_bf16_f32 v127, v128, v129
	v_cvt_pk_bf16_f32 v128, v122, v123
	v_cvt_pk_bf16_f32 v129, v124, v125
	global_store_dwordx4 v[148:149], v[126:129], off
	v_cvt_pk_bf16_f32 v118, v118, v119
	v_cvt_pk_bf16_f32 v119, v120, v121
	v_cvt_pk_bf16_f32 v120, v110, v111
	v_or_b32_e32 v110, 16, v158
	v_ashrrev_i32_e32 v111, 31, v110
	v_lshlrev_b64 v[110:111], 12, v[110:111]
	v_lshl_add_u64 v[110:111], s[8:9], 0, v[110:111]
	v_cvt_pk_bf16_f32 v121, v112, v113
	global_store_dwordx4 v[148:149], v[118:121], off offset:256
	s_mov_b32 s71, s26
	s_mov_b32 s42, s36
	v_lshl_add_u64 v[118:119], v[110:111], 0, v[162:163]
	v_cvt_pk_bf16_f32 v110, v114, v115
	v_cvt_pk_bf16_f32 v111, v116, v117
	v_cvt_pk_bf16_f32 v112, v106, v107
	v_cvt_pk_bf16_f32 v113, v108, v109
	global_store_dwordx4 v[118:119], v[110:113], off
	v_cvt_pk_bf16_f32 v102, v102, v103
	v_cvt_pk_bf16_f32 v103, v104, v105
	v_cvt_pk_bf16_f32 v104, v94, v95
	v_or_b32_e32 v94, 32, v158
	v_ashrrev_i32_e32 v95, 31, v94
	v_lshlrev_b64 v[94:95], 12, v[94:95]
	v_lshl_add_u64 v[94:95], s[8:9], 0, v[94:95]
	v_cvt_pk_bf16_f32 v105, v96, v97
	global_store_dwordx4 v[118:119], v[102:105], off offset:256
	s_mov_b64 s[46:47], s[40:41]
	s_mov_b64 s[44:45], s[38:39]
	v_lshl_add_u64 v[102:103], v[94:95], 0, v[162:163]
	v_cvt_pk_bf16_f32 v94, v98, v99
	v_cvt_pk_bf16_f32 v95, v100, v101
	v_cvt_pk_bf16_f32 v96, v90, v91
	v_cvt_pk_bf16_f32 v97, v92, v93
	global_store_dwordx4 v[102:103], v[94:97], off
	v_cvt_pk_bf16_f32 v86, v86, v87
	v_cvt_pk_bf16_f32 v87, v88, v89
	v_cvt_pk_bf16_f32 v88, v78, v79
	v_or_b32_e32 v78, 48, v158
	v_ashrrev_i32_e32 v79, 31, v78
	v_lshlrev_b64 v[78:79], 12, v[78:79]
	v_lshl_add_u64 v[78:79], s[8:9], 0, v[78:79]
	v_cvt_pk_bf16_f32 v89, v80, v81
	global_store_dwordx4 v[102:103], v[86:89], off offset:256
	s_nop 1
	v_lshl_add_u64 v[86:87], v[78:79], 0, v[162:163]
	v_cvt_pk_bf16_f32 v78, v82, v83
	v_cvt_pk_bf16_f32 v79, v84, v85
	v_cvt_pk_bf16_f32 v80, v74, v75
	v_cvt_pk_bf16_f32 v81, v76, v77
	global_store_dwordx4 v[86:87], v[78:81], off
	v_cvt_pk_bf16_f32 v70, v70, v71
	v_cvt_pk_bf16_f32 v71, v72, v73
	v_cvt_pk_bf16_f32 v72, v66, v67
	v_cvt_pk_bf16_f32 v73, v68, v69
	global_store_dwordx4 v[86:87], v[70:73], off offset:256
	v_cvt_pk_bf16_f32 v62, v62, v63
	v_cvt_pk_bf16_f32 v63, v64, v65
	v_cvt_pk_bf16_f32 v64, v58, v59
	v_add_co_u32_e32 v58, vcc, s67, v148
	v_lshl_add_u64 v[66:67], v[148:149], 0, s[6:7]
	s_nop 0
	v_addc_co_u32_e32 v59, vcc, 0, v149, vcc
	v_cvt_pk_bf16_f32 v65, v60, v61
	global_store_dwordx4 v[58:59], v[62:65], off
	v_cvt_pk_bf16_f32 v50, v50, v51
	v_cvt_pk_bf16_f32 v51, v52, v53
	v_cvt_pk_bf16_f32 v52, v42, v43
	v_cvt_pk_bf16_f32 v53, v44, v45
	global_store_dwordx4 v[66:67], v[50:53], off offset:256
	v_cvt_pk_bf16_f32 v42, v54, v55
	v_cvt_pk_bf16_f32 v43, v56, v57
	v_cvt_pk_bf16_f32 v44, v46, v47
	v_add_co_u32_e32 v46, vcc, s68, v148
	s_nop 0
	v_lshl_add_u64 v[50:51], v[148:149], 0, s[16:17]
	v_addc_co_u32_e32 v47, vcc, 0, v149, vcc
	v_cvt_pk_bf16_f32 v45, v48, v49
	global_store_dwordx4 v[46:47], v[42:45], off
	v_cvt_pk_bf16_f32 v34, v34, v35
	v_cvt_pk_bf16_f32 v35, v36, v37
	v_cvt_pk_bf16_f32 v36, v26, v27
	v_cvt_pk_bf16_f32 v37, v28, v29
	global_store_dwordx4 v[50:51], v[34:37], off offset:256
	v_cvt_pk_bf16_f32 v26, v38, v39
	v_cvt_pk_bf16_f32 v27, v40, v41
	v_cvt_pk_bf16_f32 v28, v30, v31
	v_add_co_u32_e32 v30, vcc, s69, v148
	s_nop 0
	v_lshl_add_u64 v[34:35], v[148:149], 0, s[18:19]
	v_addc_co_u32_e32 v31, vcc, 0, v149, vcc
	v_cvt_pk_bf16_f32 v29, v32, v33
	global_store_dwordx4 v[30:31], v[26:29], off
	v_cvt_pk_bf16_f32 v18, v18, v19
	v_cvt_pk_bf16_f32 v19, v20, v21
	v_cvt_pk_bf16_f32 v20, v10, v11
	v_cvt_pk_bf16_f32 v21, v12, v13
	global_store_dwordx4 v[34:35], v[18:21], off offset:256
	v_cvt_pk_bf16_f32 v10, v22, v23
	v_cvt_pk_bf16_f32 v11, v24, v25
	v_cvt_pk_bf16_f32 v12, v14, v15
	v_add_co_u32_e32 v14, vcc, s70, v148
	s_nop 0
	v_lshl_add_u64 v[18:19], v[148:149], 0, s[24:25]
	v_addc_co_u32_e32 v15, vcc, 0, v149, vcc
	s_and_b64 vcc, exec, s[0:1]
	v_cvt_pk_bf16_f32 v13, v16, v17
	global_store_dwordx4 v[14:15], v[10:13], off
	v_cvt_pk_bf16_f32 v6, v6, v7
	v_cvt_pk_bf16_f32 v7, v8, v9
	v_cvt_pk_bf16_f32 v8, v2, v3
	v_cvt_pk_bf16_f32 v9, v4, v5
	global_store_dwordx4 v[18:19], v[6:9], off offset:256
	s_cbranch_vccz .LBB0_358
	s_waitcnt vmcnt(0)
	s_cmpk_gt_u32 s3, 0xff
	s_cbranch_scc1 .LBB0_369
	s_barrier

.LBB0_901:
	s_add_u32 s8, s56, 0x8000000
	s_addc_u32 s9, s57, 0
	s_lshl_b32 s10, s10, 5
	s_and_b32 s19, s10, 0x60
	s_mov_b64 s[10:11], 0x80
	s_add_i32 m0, s34, 0x18000
	v_lshl_add_u64 v[8:9], v[8:9], 0, s[10:11]
	s_lshl_b32 s18, s1, 13
	s_lshl_b32 s20, s19, 7
	s_waitcnt vmcnt(4)
	s_barrier
	global_load_lds_dwordx4 v[8:9], off
	v_lshl_add_u64 v[6:7], v[6:7], 0, s[10:11]
	s_add_i32 m0, s34, 0x1a000
	s_add_i32 s48, s34, 0x8000
	s_add_i32 s49, s34, 0xa000
	global_load_lds_dwordx4 v[6:7], off
	v_lshl_add_u64 v[4:5], v[4:5], 0, s[10:11]
	s_mov_b32 m0, s48
	s_add_u32 s16, s42, 0x80080
	global_load_lds_dwordx4 v[4:5], off
	v_lshl_add_u64 v[2:3], v[2:3], 0, s[10:11]
	s_mov_b32 m0, s49
	s_addc_u32 s17, s43, 0
	global_load_lds_dwordx4 v[2:3], off
	s_add_i32 m0, s34, 0x1c000
	v_lshl_add_u64 v[2:3], s[16:17], 0, v[132:133]
	global_load_lds_dwordx4 v[2:3], off
	v_lshl_add_u64 v[2:3], s[16:17], 0, v[136:137]
	s_add_i32 m0, s34, 0x1e000
	s_sext_i32_i8 s65, s0
	global_load_lds_dwordx4 v[2:3], off
	v_and_b32_e32 v2, 15, v10
	v_lshlrev_b32_e32 v3, 1, v14
	v_lshlrev_b32_e32 v4, 2, v10
	v_lshlrev_b32_e32 v5, 6, v10
	s_movk_i32 s0, 0x3c0
	v_lshl_or_b32 v1, s1, 6, v2
	v_lshl_or_b32 v2, v2, 6, v3
	v_and_b32_e32 v4, 32, v4
	v_and_or_b32 v3, v5, s0, v3
	v_bitop3_b32 v147, s20, v3, v4 bitop3:0xf6
	v_lshlrev_b32_e32 v3, 9, v10
	v_bitop3_b32 v2, v2, s18, v4 bitop3:0xde
	v_and_b32_e32 v3, 0x70000, v3
	v_lshlrev_b32_e32 v4, 12, v13
	v_or3_b32 v3, v11, v3, v4
	v_add_u32_e32 v138, v3, v12
	v_lshlrev_b32_e32 v3, 5, v15
	s_waitcnt vmcnt(6)
	v_and_b32_e32 v3, 0xf0000, v3
	v_or3_b32 v3, v11, v3, v4
	s_add_i32 s51, 0, 0x10000
	s_add_i32 s60, 0, 0x14000
	s_ashr_i32 s50, s28, 31
	v_or_b32_e32 v150, s19, v14
	v_mov_b32_e32 v139, v133
	v_add_u32_e32 v140, v3, v12
	v_mov_b32_e32 v141, v133
	v_mov_b64_e32 v[142:143], 0x400
	v_mov_b64_e32 v[144:145], 0x3ff
	v_add_u32_e32 v151, s51, v147
	v_add_u32_e32 v152, 0, v2
	v_add_u32_e32 v153, s60, v147
	s_mov_b32 s61, 0x80000
	s_mov_b64 s[16:17], 0x90000
	s_mov_b32 s62, 0x90000
	s_mov_b64 s[18:19], 0xa0000
	s_mov_b32 s63, 0xa0000
	s_mov_b64 s[20:21], 0xb0000
	s_mov_b32 s64, 0xb0000
	s_barrier
	s_mov_b32 s99, 0

.LBB0_908:
	s_ashr_i32 s25, s24, 31
	v_cmp_lt_i64_e32 vcc, s[26:27], v[142:143]
	s_lshl_b64 s[26:27], s[24:25], 20
	s_add_u32 s26, s56, s26
	s_addc_u32 s27, s57, s27
	s_and_b64 s[36:37], vcc, exec
	s_cselect_b32 s25, s27, s41
	s_cselect_b32 s66, s26, s40
	s_ashr_i32 s23, s22, 31
	s_lshl_b64 s[36:37], s[22:23], 20
	s_add_u32 s36, s30, s36
	s_addc_u32 s37, s31, s37
	s_and_b64 s[44:45], vcc, exec
	s_cselect_b32 s23, s37, s43
	s_cselect_b32 s67, s36, s42
	s_add_u32 s40, s40, 0x80080
	s_addc_u32 s41, s41, 0
	s_add_u32 s68, s42, 0x100
	v_mov_b32_e32 v2, 0
	s_addc_u32 s69, s43, 0
	s_mov_b32 s70, -2
	v_mov_b32_e32 v3, v2
	v_mov_b32_e32 v4, v2
	v_mov_b32_e32 v5, v2
	v_mov_b32_e32 v6, v2
	v_mov_b32_e32 v7, v2
	v_mov_b32_e32 v8, v2
	v_mov_b32_e32 v9, v2
	v_mov_b32_e32 v10, v2
	v_mov_b32_e32 v11, v2
	v_mov_b32_e32 v12, v2
	v_mov_b32_e32 v13, v2
	v_mov_b32_e32 v18, v2
	v_mov_b32_e32 v19, v2
	v_mov_b32_e32 v20, v2
	v_mov_b32_e32 v21, v2
	v_mov_b32_e32 v26, v2
	v_mov_b32_e32 v27, v2
	v_mov_b32_e32 v28, v2
	v_mov_b32_e32 v29, v2
	v_mov_b32_e32 v34, v2
	v_mov_b32_e32 v35, v2
	v_mov_b32_e32 v36, v2
	v_mov_b32_e32 v37, v2
	v_mov_b32_e32 v42, v2
	v_mov_b32_e32 v43, v2
	v_mov_b32_e32 v44, v2
	v_mov_b32_e32 v45, v2
	v_mov_b32_e32 v50, v2
	v_mov_b32_e32 v51, v2
	v_mov_b32_e32 v52, v2
	v_mov_b32_e32 v53, v2
	v_mov_b32_e32 v14, v2
	v_mov_b32_e32 v15, v2
	v_mov_b32_e32 v16, v2
	v_mov_b32_e32 v17, v2
	v_mov_b32_e32 v22, v2
	v_mov_b32_e32 v23, v2
	v_mov_b32_e32 v24, v2
	v_mov_b32_e32 v25, v2
	v_mov_b32_e32 v30, v2
	v_mov_b32_e32 v31, v2
	v_mov_b32_e32 v32, v2
	v_mov_b32_e32 v33, v2
	v_mov_b32_e32 v38, v2
	v_mov_b32_e32 v39, v2
	v_mov_b32_e32 v40, v2
	v_mov_b32_e32 v41, v2
	v_mov_b32_e32 v46, v2
	v_mov_b32_e32 v47, v2
	v_mov_b32_e32 v48, v2
	v_mov_b32_e32 v49, v2
	v_mov_b32_e32 v54, v2
	v_mov_b32_e32 v55, v2
	v_mov_b32_e32 v56, v2
	v_mov_b32_e32 v57, v2
	v_mov_b32_e32 v58, v2
	v_mov_b32_e32 v59, v2
	v_mov_b32_e32 v60, v2
	v_mov_b32_e32 v61, v2
	v_mov_b32_e32 v62, v2
	v_mov_b32_e32 v63, v2
	v_mov_b32_e32 v64, v2
	v_mov_b32_e32 v65, v2
	v_mov_b32_e32 v66, v2
	v_mov_b32_e32 v67, v2
	v_mov_b32_e32 v68, v2
	v_mov_b32_e32 v69, v2
	v_mov_b32_e32 v70, v2
	v_mov_b32_e32 v71, v2
	v_mov_b32_e32 v72, v2
	v_mov_b32_e32 v73, v2
	v_mov_b32_e32 v78, v2
	v_mov_b32_e32 v79, v2
	v_mov_b32_e32 v80, v2
	v_mov_b32_e32 v81, v2
	v_mov_b32_e32 v86, v2
	v_mov_b32_e32 v87, v2
	v_mov_b32_e32 v88, v2
	v_mov_b32_e32 v89, v2
	v_mov_b32_e32 v94, v2
	v_mov_b32_e32 v95, v2
	v_mov_b32_e32 v96, v2
	v_mov_b32_e32 v97, v2
	v_mov_b32_e32 v102, v2
	v_mov_b32_e32 v103, v2
	v_mov_b32_e32 v104, v2
	v_mov_b32_e32 v105, v2
	v_mov_b32_e32 v110, v2
	v_mov_b32_e32 v111, v2
	v_mov_b32_e32 v112, v2
	v_mov_b32_e32 v113, v2
	v_mov_b32_e32 v118, v2
	v_mov_b32_e32 v119, v2
	v_mov_b32_e32 v120, v2
	v_mov_b32_e32 v121, v2
	v_mov_b32_e32 v74, v2
	v_mov_b32_e32 v75, v2
	v_mov_b32_e32 v76, v2
	v_mov_b32_e32 v77, v2
	v_mov_b32_e32 v82, v2
	v_mov_b32_e32 v83, v2
	v_mov_b32_e32 v84, v2
	v_mov_b32_e32 v85, v2
	v_mov_b32_e32 v90, v2
	v_mov_b32_e32 v91, v2
	v_mov_b32_e32 v92, v2
	v_mov_b32_e32 v93, v2
	v_mov_b32_e32 v98, v2
	v_mov_b32_e32 v99, v2
	v_mov_b32_e32 v100, v2
	v_mov_b32_e32 v101, v2
	v_mov_b32_e32 v106, v2
	v_mov_b32_e32 v107, v2
	v_mov_b32_e32 v108, v2
	v_mov_b32_e32 v109, v2
	v_mov_b32_e32 v114, v2
	v_mov_b32_e32 v115, v2
	v_mov_b32_e32 v116, v2
	v_mov_b32_e32 v117, v2
	v_mov_b32_e32 v122, v2
	v_mov_b32_e32 v123, v2
	v_mov_b32_e32 v124, v2
	v_mov_b32_e32 v125, v2
	v_mov_b32_e32 v126, v2
	v_mov_b32_e32 v127, v2
	v_mov_b32_e32 v128, v2
	v_mov_b32_e32 v129, v2
	s_cmp_eq_u32 s99, 0
	s_cbranch_scc1 .LBB0_909
	ds_read_b128 v[154:157], v151
	ds_read_b128 v[158:161], v151 offset:1024
	ds_read_b128 v[162:165], v151 offset:2048
	ds_read_b128 v[166:169], v151 offset:3072
	s_add_u32 s42, s40, 0xfff80080
	s_addc_u32 s43, s41, -1
	s_cmp_eq_u32 s70, 28
	s_cselect_b32 s45, s25, s43
	s_cselect_b32 s44, s66, s42
	s_cselect_b32 s43, s23, s69
	s_cselect_b32 s42, s67, s68
	v_lshl_add_u64 v[148:149], s[40:41], 0, v[138:139]
	s_add_i32 m0, s34, 0xc000
	ds_read_b128 v[170:173], v152
	ds_read_b128 v[174:177], v152 offset:1024
	ds_read_b128 v[178:181], v152 offset:2048
	ds_read_b128 v[182:185], v152 offset:3072
	ds_read_b128 v[186:189], v152 offset:4096
	ds_read_b128 v[190:193], v152 offset:5120
	ds_read_b128 v[194:197], v152 offset:6144
	ds_read_b128 v[198:201], v152 offset:7168
	v_lshl_add_u64 v[148:149], s[40:41], 0, v[140:141]
	s_add_i32 m0, s34, 0xe000
	s_nop 0
	s_waitcnt lgkmcnt(8)
	s_barrier
	s_waitcnt lgkmcnt(0)
	s_setprio 1
	s_waitcnt lgkmcnt(0)
	v_mfma_f32_16x16x32_bf16 v[126:129], v[154:157], v[170:173], v[126:129]
	v_mfma_f32_16x16x32_bf16 v[122:125], v[162:165], v[170:173], v[122:125]
	v_mfma_f32_16x16x32_bf16 v[114:117], v[154:157], v[178:181], v[114:117]
	v_mfma_f32_16x16x32_bf16 v[106:109], v[162:165], v[178:181], v[106:109]
	v_mfma_f32_16x16x32_bf16 v[98:101], v[154:157], v[186:189], v[98:101]
	v_mfma_f32_16x16x32_bf16 v[90:93], v[162:165], v[186:189], v[90:93]
	v_mfma_f32_16x16x32_bf16 v[82:85], v[154:157], v[194:197], v[82:85]
	v_mfma_f32_16x16x32_bf16 v[74:77], v[162:165], v[194:197], v[74:77]
	v_mfma_f32_16x16x32_bf16 v[126:129], v[158:161], v[174:177], v[126:129]
	v_mfma_f32_16x16x32_bf16 v[122:125], v[166:169], v[174:177], v[122:125]
	v_mfma_f32_16x16x32_bf16 v[114:117], v[158:161], v[182:185], v[114:117]
	v_mfma_f32_16x16x32_bf16 v[106:109], v[166:169], v[182:185], v[106:109]
	v_mfma_f32_16x16x32_bf16 v[98:101], v[158:161], v[190:193], v[98:101]
	v_mfma_f32_16x16x32_bf16 v[90:93], v[166:169], v[190:193], v[90:93]
	v_mfma_f32_16x16x32_bf16 v[82:85], v[158:161], v[198:201], v[82:85]
	v_mfma_f32_16x16x32_bf16 v[74:77], v[166:169], v[198:201], v[74:77]
	s_setprio 0
	s_barrier
	s_add_i32 s71, s51, s33
	v_lshl_add_u64 v[148:149], s[42:43], 0, v[132:133]
	s_mov_b32 m0, s71
	ds_read_b128 v[202:205], v153
	ds_read_b128 v[206:209], v153 offset:1024
	ds_read_b128 v[210:213], v153 offset:2048
	ds_read_b128 v[214:217], v153 offset:3072
	global_load_lds_dwordx4 v[148:149], off
	v_lshl_add_u64 v[218:219], s[42:43], 0, v[136:137]
	s_add_i32 m0, s71, 0x2000
	s_nop 0
	global_load_lds_dwordx4 v[218:219], off
	s_barrier
	s_waitcnt lgkmcnt(0)
	s_setprio 1
	s_waitcnt lgkmcnt(0)
	v_mfma_f32_16x16x32_bf16 v[118:121], v[202:205], v[170:173], v[118:121]
	v_mfma_f32_16x16x32_bf16 v[110:113], v[210:213], v[170:173], v[110:113]
	v_mfma_f32_16x16x32_bf16 v[102:105], v[202:205], v[178:181], v[102:105]
	v_mfma_f32_16x16x32_bf16 v[94:97], v[210:213], v[178:181], v[94:97]
	v_mfma_f32_16x16x32_bf16 v[86:89], v[202:205], v[186:189], v[86:89]
	v_mfma_f32_16x16x32_bf16 v[78:81], v[210:213], v[186:189], v[78:81]
	v_mfma_f32_16x16x32_bf16 v[70:73], v[202:205], v[194:197], v[70:73]
	v_mfma_f32_16x16x32_bf16 v[66:69], v[210:213], v[194:197], v[66:69]
	v_mfma_f32_16x16x32_bf16 v[118:121], v[206:209], v[174:177], v[118:121]
	v_mfma_f32_16x16x32_bf16 v[110:113], v[214:217], v[174:177], v[110:113]
	v_mfma_f32_16x16x32_bf16 v[102:105], v[206:209], v[182:185], v[102:105]
	v_mfma_f32_16x16x32_bf16 v[94:97], v[214:217], v[182:185], v[94:97]
	v_mfma_f32_16x16x32_bf16 v[86:89], v[206:209], v[190:193], v[86:89]
	v_mfma_f32_16x16x32_bf16 v[78:81], v[214:217], v[190:193], v[78:81]
	v_mfma_f32_16x16x32_bf16 v[70:73], v[206:209], v[198:201], v[70:73]
	v_mfma_f32_16x16x32_bf16 v[66:69], v[214:217], v[198:201], v[66:69]
	s_setprio 0
	s_mov_b32 m0, s34
	v_lshl_add_u64 v[220:221], s[44:45], 0, v[130:131]
	s_barrier
	ds_read_b128 v[170:173], v152 offset:16384
	ds_read_b128 v[174:177], v152 offset:17408
	ds_read_b128 v[178:181], v152 offset:18432
	ds_read_b128 v[182:185], v152 offset:19456
	ds_read_b128 v[186:189], v152 offset:20480
	ds_read_b128 v[190:193], v152 offset:21504
	ds_read_b128 v[194:197], v152 offset:22528
	ds_read_b128 v[198:201], v152 offset:23552
	global_load_lds_dwordx4 v[220:221], off
	v_lshl_add_u64 v[222:223], s[44:45], 0, v[134:135]
	s_mov_b32 m0, s35
	s_nop 0
	global_load_lds_dwordx4 v[222:223], off
	s_barrier
	s_waitcnt lgkmcnt(0)
	s_setprio 1
	s_waitcnt lgkmcnt(0)
	v_mfma_f32_16x16x32_bf16 v[62:65], v[154:157], v[170:173], v[62:65]
	v_mfma_f32_16x16x32_bf16 v[58:61], v[162:165], v[170:173], v[58:61]
	v_mfma_f32_16x16x32_bf16 v[54:57], v[154:157], v[178:181], v[54:57]
	v_mfma_f32_16x16x32_bf16 v[46:49], v[162:165], v[178:181], v[46:49]
	v_mfma_f32_16x16x32_bf16 v[38:41], v[154:157], v[186:189], v[38:41]
	v_mfma_f32_16x16x32_bf16 v[30:33], v[162:165], v[186:189], v[30:33]
	v_mfma_f32_16x16x32_bf16 v[22:25], v[154:157], v[194:197], v[22:25]
	v_mfma_f32_16x16x32_bf16 v[14:17], v[162:165], v[194:197], v[14:17]
	v_mfma_f32_16x16x32_bf16 v[62:65], v[158:161], v[174:177], v[62:65]
	v_mfma_f32_16x16x32_bf16 v[58:61], v[166:169], v[174:177], v[58:61]
	v_mfma_f32_16x16x32_bf16 v[54:57], v[158:161], v[182:185], v[54:57]
	v_mfma_f32_16x16x32_bf16 v[46:49], v[166:169], v[182:185], v[46:49]
	v_mfma_f32_16x16x32_bf16 v[38:41], v[158:161], v[190:193], v[38:41]
	v_mfma_f32_16x16x32_bf16 v[30:33], v[166:169], v[190:193], v[30:33]
	v_mfma_f32_16x16x32_bf16 v[22:25], v[158:161], v[198:201], v[22:25]
	v_mfma_f32_16x16x32_bf16 v[14:17], v[166:169], v[198:201], v[14:17]
	s_setprio 0
	s_barrier
	s_add_u32 s72, s42, 0x80000
	s_addc_u32 s73, s43, 0
	s_add_i32 s71, s60, s33
	v_lshl_add_u64 v[154:155], s[72:73], 0, v[132:133]
	s_mov_b32 m0, s71
	s_nop 0
	global_load_lds_dwordx4 v[154:155], off
	v_lshl_add_u64 v[154:155], s[72:73], 0, v[136:137]
	s_add_i32 m0, s71, 0x2000
	s_nop 0
	global_load_lds_dwordx4 v[154:155], off
	s_waitcnt vmcnt(22)
	s_barrier
	s_setprio 1
	v_mfma_f32_16x16x32_bf16 v[50:53], v[202:205], v[170:173], v[50:53]
	v_mfma_f32_16x16x32_bf16 v[42:45], v[210:213], v[170:173], v[42:45]
	v_mfma_f32_16x16x32_bf16 v[34:37], v[202:205], v[178:181], v[34:37]
	v_mfma_f32_16x16x32_bf16 v[26:29], v[210:213], v[178:181], v[26:29]
	v_mfma_f32_16x16x32_bf16 v[18:21], v[202:205], v[186:189], v[18:21]
	v_mfma_f32_16x16x32_bf16 v[10:13], v[210:213], v[186:189], v[10:13]
	v_mfma_f32_16x16x32_bf16 v[6:9], v[202:205], v[194:197], v[6:9]
	v_mfma_f32_16x16x32_bf16 v[2:5], v[210:213], v[194:197], v[2:5]
	v_mfma_f32_16x16x32_bf16 v[50:53], v[206:209], v[174:177], v[50:53]
	v_mfma_f32_16x16x32_bf16 v[42:45], v[214:217], v[174:177], v[42:45]
	v_mfma_f32_16x16x32_bf16 v[34:37], v[206:209], v[182:185], v[34:37]
	v_mfma_f32_16x16x32_bf16 v[26:29], v[214:217], v[182:185], v[26:29]
	v_mfma_f32_16x16x32_bf16 v[18:21], v[206:209], v[190:193], v[18:21]
	v_mfma_f32_16x16x32_bf16 v[10:13], v[214:217], v[190:193], v[10:13]
	v_mfma_f32_16x16x32_bf16 v[6:9], v[206:209], v[198:201], v[6:9]
	v_mfma_f32_16x16x32_bf16 v[2:5], v[214:217], v[198:201], v[2:5]
	s_setprio 0
	s_add_i32 s71, 0, 0x18000
	v_add_u32_e32 v166, s71, v147
	s_barrier
	s_branch .Ltb_mid_p9

.Ltb_mid_p9:
	ds_read_b128 v[154:157], v166
	ds_read_b128 v[158:161], v166 offset:1024
	ds_read_b128 v[162:165], v166 offset:2048
	ds_read_b128 v[166:169], v166 offset:3072
	s_add_u32 s44, s44, 0x80000
	s_addc_u32 s45, s45, 0
	s_mov_b32 m0, s39
	v_lshl_add_u64 v[202:203], s[44:45], 0, v[130:131]
	ds_read_b128 v[170:173], v152 offset:32768
	ds_read_b128 v[174:177], v152 offset:33792
	ds_read_b128 v[178:181], v152 offset:34816
	ds_read_b128 v[182:185], v152 offset:35840
	ds_read_b128 v[186:189], v152 offset:36864
	ds_read_b128 v[190:193], v152 offset:37888
	ds_read_b128 v[194:197], v152 offset:38912
	ds_read_b128 v[198:201], v152 offset:39936
	global_load_lds_dwordx4 v[202:203], off
	v_lshl_add_u64 v[202:203], s[44:45], 0, v[134:135]
	s_mov_b32 m0, s46
	s_nop 0
	global_load_lds_dwordx4 v[202:203], off
	s_waitcnt lgkmcnt(8)
	s_barrier
	s_waitcnt lgkmcnt(0)
	s_setprio 1
	s_waitcnt lgkmcnt(0)
	v_mfma_f32_16x16x32_bf16 v[126:129], v[154:157], v[170:173], v[126:129]
	v_mfma_f32_16x16x32_bf16 v[122:125], v[162:165], v[170:173], v[122:125]
	v_mfma_f32_16x16x32_bf16 v[114:117], v[154:157], v[178:181], v[114:117]
	v_mfma_f32_16x16x32_bf16 v[106:109], v[162:165], v[178:181], v[106:109]
	v_mfma_f32_16x16x32_bf16 v[98:101], v[154:157], v[186:189], v[98:101]
	v_mfma_f32_16x16x32_bf16 v[90:93], v[162:165], v[186:189], v[90:93]
	v_mfma_f32_16x16x32_bf16 v[82:85], v[154:157], v[194:197], v[82:85]
	v_mfma_f32_16x16x32_bf16 v[74:77], v[162:165], v[194:197], v[74:77]
	v_mfma_f32_16x16x32_bf16 v[126:129], v[158:161], v[174:177], v[126:129]
	v_mfma_f32_16x16x32_bf16 v[122:125], v[166:169], v[174:177], v[122:125]
	v_mfma_f32_16x16x32_bf16 v[114:117], v[158:161], v[182:185], v[114:117]
	v_mfma_f32_16x16x32_bf16 v[106:109], v[166:169], v[182:185], v[106:109]
	v_mfma_f32_16x16x32_bf16 v[98:101], v[158:161], v[190:193], v[98:101]
	v_mfma_f32_16x16x32_bf16 v[90:93], v[166:169], v[190:193], v[90:93]
	v_mfma_f32_16x16x32_bf16 v[82:85], v[158:161], v[198:201], v[82:85]
	v_mfma_f32_16x16x32_bf16 v[74:77], v[166:169], v[198:201], v[74:77]
	s_setprio 0
	s_barrier
	s_add_i32 s44, 0, 0x1c000
	s_add_i32 s45, s71, s33
	v_add_u32_e32 v214, s44, v147
	v_lshl_add_u64 v[148:149], v[148:149], 0, s[10:11]
	s_mov_b32 m0, s45
	ds_read_b128 v[202:205], v214
	ds_read_b128 v[206:209], v214 offset:1024
	ds_read_b128 v[210:213], v214 offset:2048
	ds_read_b128 v[214:217], v214 offset:3072
	global_load_lds_dwordx4 v[148:149], off
	v_lshl_add_u64 v[148:149], v[218:219], 0, s[10:11]
	s_add_i32 m0, s45, 0x2000
	s_nop 0
	global_load_lds_dwordx4 v[148:149], off
	s_barrier
	s_waitcnt lgkmcnt(0)
	s_setprio 1
	s_waitcnt lgkmcnt(0)
	v_mfma_f32_16x16x32_bf16 v[118:121], v[202:205], v[170:173], v[118:121]
	v_mfma_f32_16x16x32_bf16 v[110:113], v[210:213], v[170:173], v[110:113]
	v_mfma_f32_16x16x32_bf16 v[102:105], v[202:205], v[178:181], v[102:105]
	v_mfma_f32_16x16x32_bf16 v[94:97], v[210:213], v[178:181], v[94:97]
	v_mfma_f32_16x16x32_bf16 v[86:89], v[202:205], v[186:189], v[86:89]
	v_mfma_f32_16x16x32_bf16 v[78:81], v[210:213], v[186:189], v[78:81]
	v_mfma_f32_16x16x32_bf16 v[70:73], v[202:205], v[194:197], v[70:73]
	v_mfma_f32_16x16x32_bf16 v[66:69], v[210:213], v[194:197], v[66:69]
	v_mfma_f32_16x16x32_bf16 v[118:121], v[206:209], v[174:177], v[118:121]
	v_mfma_f32_16x16x32_bf16 v[110:113], v[214:217], v[174:177], v[110:113]
	v_mfma_f32_16x16x32_bf16 v[102:105], v[206:209], v[182:185], v[102:105]
	v_mfma_f32_16x16x32_bf16 v[94:97], v[214:217], v[182:185], v[94:97]
	v_mfma_f32_16x16x32_bf16 v[86:89], v[206:209], v[190:193], v[86:89]
	v_mfma_f32_16x16x32_bf16 v[78:81], v[214:217], v[190:193], v[78:81]
	v_mfma_f32_16x16x32_bf16 v[70:73], v[206:209], v[198:201], v[70:73]
	v_mfma_f32_16x16x32_bf16 v[66:69], v[214:217], v[198:201], v[66:69]
	s_setprio 0
	s_mov_b32 m0, s48
	v_lshl_add_u64 v[148:149], v[220:221], 0, s[10:11]
	s_barrier
	ds_read_b128 v[170:173], v152 offset:49152
	ds_read_b128 v[174:177], v152 offset:50176
	ds_read_b128 v[178:181], v152 offset:51200
	ds_read_b128 v[182:185], v152 offset:52224
	ds_read_b128 v[186:189], v152 offset:53248
	ds_read_b128 v[190:193], v152 offset:54272
	ds_read_b128 v[194:197], v152 offset:55296
	ds_read_b128 v[198:201], v152 offset:56320
	global_load_lds_dwordx4 v[148:149], off
	v_lshl_add_u64 v[148:149], v[222:223], 0, s[10:11]
	s_mov_b32 m0, s49
	s_nop 0
	global_load_lds_dwordx4 v[148:149], off
	s_barrier
	s_waitcnt lgkmcnt(0)
	s_setprio 1
	s_waitcnt lgkmcnt(0)
	v_mfma_f32_16x16x32_bf16 v[62:65], v[154:157], v[170:173], v[62:65]
	v_mfma_f32_16x16x32_bf16 v[58:61], v[162:165], v[170:173], v[58:61]
	v_mfma_f32_16x16x32_bf16 v[54:57], v[154:157], v[178:181], v[54:57]
	v_mfma_f32_16x16x32_bf16 v[46:49], v[162:165], v[178:181], v[46:49]
	v_mfma_f32_16x16x32_bf16 v[38:41], v[154:157], v[186:189], v[38:41]
	v_mfma_f32_16x16x32_bf16 v[30:33], v[162:165], v[186:189], v[30:33]
	v_mfma_f32_16x16x32_bf16 v[22:25], v[154:157], v[194:197], v[22:25]
	v_mfma_f32_16x16x32_bf16 v[14:17], v[162:165], v[194:197], v[14:17]
	v_mfma_f32_16x16x32_bf16 v[62:65], v[158:161], v[174:177], v[62:65]
	v_mfma_f32_16x16x32_bf16 v[58:61], v[166:169], v[174:177], v[58:61]
	v_mfma_f32_16x16x32_bf16 v[54:57], v[158:161], v[182:185], v[54:57]
	v_mfma_f32_16x16x32_bf16 v[46:49], v[166:169], v[182:185], v[46:49]
	v_mfma_f32_16x16x32_bf16 v[38:41], v[158:161], v[190:193], v[38:41]
	v_mfma_f32_16x16x32_bf16 v[30:33], v[166:169], v[190:193], v[30:33]
	v_mfma_f32_16x16x32_bf16 v[22:25], v[158:161], v[198:201], v[22:25]
	v_mfma_f32_16x16x32_bf16 v[14:17], v[166:169], v[198:201], v[14:17]
	s_setprio 0
	s_barrier
	s_add_u32 s42, s42, 0x80080
	s_addc_u32 s43, s43, 0
	s_add_i32 s44, s44, s33
	v_lshl_add_u64 v[148:149], s[42:43], 0, v[132:133]
	s_mov_b32 m0, s44
	s_nop 0
	global_load_lds_dwordx4 v[148:149], off
	v_lshl_add_u64 v[148:149], s[42:43], 0, v[136:137]
	s_add_i32 m0, s44, 0x2000
	s_nop 0
	global_load_lds_dwordx4 v[148:149], off
	s_waitcnt vmcnt(6)
	s_barrier
	s_setprio 1
	v_mfma_f32_16x16x32_bf16 v[50:53], v[202:205], v[170:173], v[50:53]
	v_mfma_f32_16x16x32_bf16 v[42:45], v[210:213], v[170:173], v[42:45]
	v_mfma_f32_16x16x32_bf16 v[34:37], v[202:205], v[178:181], v[34:37]
	v_mfma_f32_16x16x32_bf16 v[26:29], v[210:213], v[178:181], v[26:29]
	v_mfma_f32_16x16x32_bf16 v[18:21], v[202:205], v[186:189], v[18:21]
	v_mfma_f32_16x16x32_bf16 v[10:13], v[210:213], v[186:189], v[10:13]
	v_mfma_f32_16x16x32_bf16 v[6:9], v[202:205], v[194:197], v[6:9]
	v_mfma_f32_16x16x32_bf16 v[2:5], v[210:213], v[194:197], v[2:5]
	v_mfma_f32_16x16x32_bf16 v[50:53], v[206:209], v[174:177], v[50:53]
	v_mfma_f32_16x16x32_bf16 v[42:45], v[214:217], v[174:177], v[42:45]
	v_mfma_f32_16x16x32_bf16 v[34:37], v[206:209], v[182:185], v[34:37]
	v_mfma_f32_16x16x32_bf16 v[26:29], v[214:217], v[182:185], v[26:29]
	v_mfma_f32_16x16x32_bf16 v[18:21], v[206:209], v[190:193], v[18:21]
	v_mfma_f32_16x16x32_bf16 v[10:13], v[214:217], v[190:193], v[10:13]
	v_mfma_f32_16x16x32_bf16 v[6:9], v[206:209], v[198:201], v[6:9]
	v_mfma_f32_16x16x32_bf16 v[2:5], v[214:217], v[198:201], v[2:5]
	s_setprio 0
	s_add_i32 s70, s70, 2
	s_add_u32 s40, s40, 0x100
	s_addc_u32 s41, s41, 0
	s_add_u32 s68, s68, 0x100
	s_addc_u32 s69, s69, 0
	s_cmp_gt_u32 s70, 29
	s_barrier
	s_cbranch_scc0 .LBB0_909
	s_add_u32 s100, s66, 0x80080
	s_addc_u32 s101, s25, 0
	v_lshl_add_u64 v[148:149], s[100:101], 0, v[138:139]
	s_add_i32 m0, s34, 0xc000
	s_nop 0
	global_load_lds_dwordx4 v[148:149], off
	v_lshl_add_u64 v[148:149], s[100:101], 0, v[140:141]
	s_add_i32 m0, s34, 0xe000
	s_nop 0
	global_load_lds_dwordx4 v[148:149], off
	s_mov_b32 s99, 1
	v_lshl_add_u32 v154, s38, 8, v1
	v_lshl_or_b32 v148, s65, 8, v150
	v_ashrrev_i32_e32 v155, 31, v154
	v_ashrrev_i32_e32 v149, 31, v148
	v_lshlrev_b64 v[156:157], 12, v[154:155]
	v_lshl_add_u64 v[156:157], s[8:9], 0, v[156:157]
	v_lshlrev_b64 v[158:159], 1, v[148:149]
	v_lshl_add_u64 v[148:149], v[156:157], 0, v[158:159]
	v_cvt_pk_bf16_f32 v126, v126, v127
	v_cvt_pk_bf16_f32 v127, v128, v129
	v_cvt_pk_bf16_f32 v128, v122, v123
	v_cvt_pk_bf16_f32 v129, v124, v125
	global_store_dwordx4 v[148:149], v[126:129], off
	v_cvt_pk_bf16_f32 v118, v118, v119
	v_cvt_pk_bf16_f32 v119, v120, v121
	v_cvt_pk_bf16_f32 v120, v110, v111
	v_or_b32_e32 v110, 16, v154
	v_ashrrev_i32_e32 v111, 31, v110
	v_lshlrev_b64 v[110:111], 12, v[110:111]
	v_lshl_add_u64 v[110:111], s[8:9], 0, v[110:111]
	v_cvt_pk_bf16_f32 v121, v112, v113
	global_store_dwordx4 v[148:149], v[118:121], off offset:256
	s_mov_b32 s65, s22
	s_mov_b32 s38, s24
	v_lshl_add_u64 v[118:119], v[110:111], 0, v[158:159]
	v_cvt_pk_bf16_f32 v110, v114, v115
	v_cvt_pk_bf16_f32 v111, v116, v117
	v_cvt_pk_bf16_f32 v112, v106, v107
	v_cvt_pk_bf16_f32 v113, v108, v109
	global_store_dwordx4 v[118:119], v[110:113], off
	v_cvt_pk_bf16_f32 v102, v102, v103
	v_cvt_pk_bf16_f32 v103, v104, v105
	v_cvt_pk_bf16_f32 v104, v94, v95
	v_or_b32_e32 v94, 32, v154
	v_ashrrev_i32_e32 v95, 31, v94
	v_lshlrev_b64 v[94:95], 12, v[94:95]
	v_lshl_add_u64 v[94:95], s[8:9], 0, v[94:95]
	v_cvt_pk_bf16_f32 v105, v96, v97
	global_store_dwordx4 v[118:119], v[102:105], off offset:256
	s_mov_b64 s[42:43], s[36:37]
	s_mov_b64 s[40:41], s[26:27]
	v_lshl_add_u64 v[102:103], v[94:95], 0, v[158:159]
	v_cvt_pk_bf16_f32 v94, v98, v99
	v_cvt_pk_bf16_f32 v95, v100, v101
	v_cvt_pk_bf16_f32 v96, v90, v91
	v_cvt_pk_bf16_f32 v97, v92, v93
	global_store_dwordx4 v[102:103], v[94:97], off
	v_cvt_pk_bf16_f32 v86, v86, v87
	v_cvt_pk_bf16_f32 v87, v88, v89
	v_cvt_pk_bf16_f32 v88, v78, v79
	v_or_b32_e32 v78, 48, v154
	v_ashrrev_i32_e32 v79, 31, v78
	v_lshlrev_b64 v[78:79], 12, v[78:79]
	v_lshl_add_u64 v[78:79], s[8:9], 0, v[78:79]
	v_cvt_pk_bf16_f32 v89, v80, v81
	global_store_dwordx4 v[102:103], v[86:89], off offset:256
	s_nop 1
	v_lshl_add_u64 v[86:87], v[78:79], 0, v[158:159]
	v_cvt_pk_bf16_f32 v78, v82, v83
	v_cvt_pk_bf16_f32 v79, v84, v85
	v_cvt_pk_bf16_f32 v80, v74, v75
	v_cvt_pk_bf16_f32 v81, v76, v77
	global_store_dwordx4 v[86:87], v[78:81], off
	v_cvt_pk_bf16_f32 v70, v70, v71
	v_cvt_pk_bf16_f32 v71, v72, v73
	v_cvt_pk_bf16_f32 v72, v66, v67
	v_cvt_pk_bf16_f32 v73, v68, v69
	global_store_dwordx4 v[86:87], v[70:73], off offset:256
	v_cvt_pk_bf16_f32 v62, v62, v63
	v_cvt_pk_bf16_f32 v63, v64, v65
	v_cvt_pk_bf16_f32 v64, v58, v59
	v_add_co_u32_e32 v58, vcc, s61, v148
	v_lshl_add_u64 v[66:67], v[148:149], 0, s[6:7]
	s_nop 0
	v_addc_co_u32_e32 v59, vcc, 0, v149, vcc
	v_cvt_pk_bf16_f32 v65, v60, v61
	global_store_dwordx4 v[58:59], v[62:65], off
	v_cvt_pk_bf16_f32 v50, v50, v51
	v_cvt_pk_bf16_f32 v51, v52, v53
	v_cvt_pk_bf16_f32 v52, v42, v43
	v_cvt_pk_bf16_f32 v53, v44, v45
	global_store_dwordx4 v[66:67], v[50:53], off offset:256
	v_cvt_pk_bf16_f32 v42, v54, v55
	v_cvt_pk_bf16_f32 v43, v56, v57
	v_cvt_pk_bf16_f32 v44, v46, v47
	v_add_co_u32_e32 v46, vcc, s62, v148
	s_nop 0
	v_lshl_add_u64 v[50:51], v[148:149], 0, s[16:17]
	v_addc_co_u32_e32 v47, vcc, 0, v149, vcc
	v_cvt_pk_bf16_f32 v45, v48, v49
	global_store_dwordx4 v[46:47], v[42:45], off
	v_cvt_pk_bf16_f32 v34, v34, v35
	v_cvt_pk_bf16_f32 v35, v36, v37
	v_cvt_pk_bf16_f32 v36, v26, v27
	v_cvt_pk_bf16_f32 v37, v28, v29
	global_store_dwordx4 v[50:51], v[34:37], off offset:256
	v_cvt_pk_bf16_f32 v26, v38, v39
	v_cvt_pk_bf16_f32 v27, v40, v41
	v_cvt_pk_bf16_f32 v28, v30, v31
	v_add_co_u32_e32 v30, vcc, s63, v148
	s_nop 0
	v_lshl_add_u64 v[34:35], v[148:149], 0, s[18:19]
	v_addc_co_u32_e32 v31, vcc, 0, v149, vcc
	v_cvt_pk_bf16_f32 v29, v32, v33
	global_store_dwordx4 v[30:31], v[26:29], off
	v_cvt_pk_bf16_f32 v18, v18, v19
	v_cvt_pk_bf16_f32 v19, v20, v21
	v_cvt_pk_bf16_f32 v20, v10, v11
	v_cvt_pk_bf16_f32 v21, v12, v13
	global_store_dwordx4 v[34:35], v[18:21], off offset:256
	v_cvt_pk_bf16_f32 v10, v22, v23
	v_cvt_pk_bf16_f32 v11, v24, v25
	v_cvt_pk_bf16_f32 v12, v14, v15
	v_add_co_u32_e32 v14, vcc, s64, v148
	s_nop 0
	v_lshl_add_u64 v[18:19], v[148:149], 0, s[20:21]
	v_addc_co_u32_e32 v15, vcc, 0, v149, vcc
	s_and_b64 vcc, exec, s[0:1]
	v_cvt_pk_bf16_f32 v13, v16, v17
	global_store_dwordx4 v[14:15], v[10:13], off
	v_cvt_pk_bf16_f32 v6, v6, v7
	v_cvt_pk_bf16_f32 v7, v8, v9
	v_cvt_pk_bf16_f32 v8, v2, v3
	v_cvt_pk_bf16_f32 v9, v4, v5
	global_store_dwordx4 v[18:19], v[6:9], off offset:256
	s_cbranch_vccz .LBB0_902
	s_waitcnt vmcnt(0)
	s_cmpk_gt_u32 s3, 0xff
	s_cbranch_scc1 .LBB0_913
	s_barrier
